# P3: weight-copy workgroups paced with s_sleep per item (they finish before the compress-GEMM workgroups anyway)
# speedup vs baseline: 1.0009x; 1.0009x over previous
.LBB0_491:
	s_sleep 32
	s_cmpk_gt_i32 s16, 0x1ff
	s_mov_b64 s[4:5], -1
	s_cbranch_scc0 .LBB0_533
	s_cmpk_gt_u32 s16, 0x11ff
	s_cbranch_scc0 .LBB0_518
	s_cmpk_gt_u32 s16, 0x21ff
	s_cbranch_scc0 .LBB0_515
	s_cmpk_gt_u32 s16, 0x23ff
	s_cbranch_scc0 .LBB0_500
	s_cmpk_gt_u32 s16, 0x277f
	s_cbranch_scc0 .LBB0_497
	s_and_b32 s4, s40, 0x3e0
	s_and_b32 s5, s53, 0x1ffc0
	v_or_b32_e32 v12, s4, v55
	v_or_b32_e32 v14, s5, v174
	v_lshlrev_b32_e32 v48, 2, v12
	s_waitcnt vmcnt(1)
	v_lshl_add_u64 v[12:13], v[10:11], 0, v[48:49]
	v_lshlrev_b32_e32 v48, 12, v14
	v_lshl_add_u64 v[40:41], v[12:13], 0, v[48:49]
	v_add_co_u32_e32 v16, vcc, 0x8000, v40
	v_add_u32_e32 v46, v81, v72
	s_nop 0
	v_addc_co_u32_e32 v17, vcc, 0, v41, vcc
	v_add_co_u32_e32 v20, vcc, 0x10000, v40
	global_load_dwordx4 v[12:15], v[40:41], off
	s_nop 0
	global_load_dwordx4 v[16:19], v[16:17], off
	v_addc_co_u32_e32 v21, vcc, 0, v41, vcc
	v_add_co_u32_e32 v24, vcc, 0x18000, v40
	v_add_u32_e32 v47, 0x420, v46
	s_nop 0
	v_addc_co_u32_e32 v25, vcc, 0, v41, vcc
	v_add_co_u32_e32 v28, vcc, 0x20000, v40
	global_load_dwordx4 v[20:23], v[20:21], off
	s_nop 0
	global_load_dwordx4 v[24:27], v[24:25], off
	v_addc_co_u32_e32 v29, vcc, 0, v41, vcc
	v_add_co_u32_e32 v32, vcc, 0x28000, v40
	v_add_u32_e32 v48, 0x428, v46
	s_nop 0
	v_addc_co_u32_e32 v33, vcc, 0, v41, vcc
	global_load_dwordx4 v[28:31], v[28:29], off
	s_nop 0
	global_load_dwordx4 v[32:35], v[32:33], off
	v_add_co_u32_e32 v36, vcc, 0x30000, v40
	v_add_u32_e32 v68, 0x840, v46
	s_nop 0
	v_addc_co_u32_e32 v37, vcc, 0, v41, vcc
	global_load_dwordx4 v[36:39], v[36:37], off
	v_add_co_u32_e32 v40, vcc, 0x38000, v40
	v_add_u32_e32 v69, 0x848, v46
	s_nop 0
	v_addc_co_u32_e32 v41, vcc, 0, v41, vcc
	global_load_dwordx4 v[40:43], v[40:41], off
	v_add_u32_e32 v70, 0xc60, v46
	v_add_u32_e32 v71, 0xc68, v46
	v_add_u32_e32 v83, 0x1080, v46
	v_add_u32_e32 v84, 0x1088, v46
	v_add_u32_e32 v85, 0x14a0, v46
	v_add_u32_e32 v86, 0x14a8, v46
	v_add_u32_e32 v87, 0x18c0, v46
	v_add_u32_e32 v88, 0x18c8, v46
	v_add_u32_e32 v89, 0x1ce0, v46
	v_add_u32_e32 v90, 0x1ce8, v46
	s_lshl_b32 s8, s5, 1
	v_lshl_add_u64 v[44:45], v[62:63], 0, s[8:9]
	s_waitcnt vmcnt(7)
	ds_write2_b32 v46, v12, v13 offset1:1
	ds_write2_b32 v46, v14, v15 offset0:2 offset1:3
	s_waitcnt vmcnt(6)
	ds_write2_b32 v47, v16, v17 offset1:1
	ds_write2_b32 v48, v18, v19 offset1:1
	s_waitcnt vmcnt(5)
	ds_write2_b32 v68, v20, v21 offset1:1
	ds_write2_b32 v69, v22, v23 offset1:1
	s_waitcnt vmcnt(4)
	ds_write2_b32 v70, v24, v25 offset1:1
	ds_write2_b32 v71, v26, v27 offset1:1
	s_waitcnt vmcnt(3)
	ds_write2_b32 v83, v28, v29 offset1:1
	ds_write2_b32 v84, v30, v31 offset1:1
	s_waitcnt vmcnt(2)
	ds_write2_b32 v85, v32, v33 offset1:1
	ds_write2_b32 v86, v34, v35 offset1:1
	s_waitcnt vmcnt(1)
	ds_write2_b32 v87, v36, v37 offset1:1
	ds_write2_b32 v88, v38, v39 offset1:1
	s_waitcnt vmcnt(0)
	ds_write2_b32 v89, v40, v41 offset1:1
	ds_write2_b32 v90, v42, v43 offset1:1
	s_waitcnt lgkmcnt(0)
	ds_read2_b32 v[16:17], v82 offset0:33 offset1:41
	ds_read2_b32 v[18:19], v82 offset1:8
	ds_read2_b32 v[20:21], v82 offset0:66 offset1:74
	ds_read2_b32 v[22:23], v82 offset0:99 offset1:107
	ds_read2_b32 v[24:25], v82 offset0:132 offset1:140
	ds_read2_b32 v[26:27], v82 offset0:165 offset1:173
	s_waitcnt lgkmcnt(4)
	v_bfe_u32 v12, v18, 16, 1
	s_waitcnt lgkmcnt(3)
	v_bfe_u32 v14, v20, 16, 1
	v_bfe_u32 v13, v16, 16, 1
	s_waitcnt lgkmcnt(2)
	v_bfe_u32 v15, v22, 16, 1
	v_add3_u32 v12, v18, v12, s26
	v_add3_u32 v14, v20, v14, s26
	s_waitcnt lgkmcnt(1)
	v_bfe_u32 v28, v24, 16, 1
	v_add3_u32 v13, v16, v13, s26
	v_add3_u32 v15, v22, v15, s26
	v_lshrrev_b32_e32 v12, 16, v12
	v_lshrrev_b32_e32 v14, 16, v14
	v_and_or_b32 v12, v13, s27, v12
	v_and_or_b32 v13, v15, s27, v14
	v_add3_u32 v14, v24, v28, s26
	ds_read2_b32 v[28:29], v82 offset0:198 offset1:206
	ds_read2_b32 v[30:31], v82 offset0:231 offset1:239
	s_waitcnt lgkmcnt(2)
	v_bfe_u32 v15, v26, 16, 1
	v_lshrrev_b32_e32 v14, 16, v14
	v_add3_u32 v15, v26, v15, s26
	v_and_or_b32 v14, v15, s27, v14
	s_waitcnt lgkmcnt(1)
	v_bfe_u32 v15, v28, 16, 1
	v_add3_u32 v15, v28, v15, s26
	s_waitcnt lgkmcnt(0)
	v_bfe_u32 v16, v30, 16, 1
	v_lshrrev_b32_e32 v15, 16, v15
	v_add3_u32 v16, v30, v16, s26
	v_and_or_b32 v15, v16, s27, v15
	v_or_b32_e32 v16, s4, v174
	v_mul_u32_u24_e32 v16, 0x300, v16
	v_lshlrev_b32_e32 v48, 1, v16
	v_lshl_add_u64 v[32:33], v[44:45], 0, v[48:49]
	global_store_dwordx4 v[32:33], v[12:15], off
	v_bfe_u32 v16, v31, 16, 1
	v_add3_u32 v16, v31, v16, s26
	v_bfe_u32 v12, v19, 16, 1
	v_add3_u32 v12, v19, v12, s26
	v_bfe_u32 v13, v17, 16, 1
	v_lshrrev_b32_e32 v12, 16, v12
	v_add3_u32 v13, v17, v13, s26
	v_and_or_b32 v12, v13, s27, v12
	v_bfe_u32 v13, v21, 16, 1
	v_add3_u32 v13, v21, v13, s26
	v_bfe_u32 v14, v23, 16, 1
	v_lshrrev_b32_e32 v13, 16, v13
	v_add3_u32 v14, v23, v14, s26
	v_and_or_b32 v13, v14, s27, v13
	v_bfe_u32 v14, v25, 16, 1
	v_add3_u32 v14, v25, v14, s26
	v_bfe_u32 v15, v27, 16, 1
	v_lshrrev_b32_e32 v14, 16, v14
	v_add3_u32 v15, v27, v15, s26
	v_and_or_b32 v14, v15, s27, v14
	v_bfe_u32 v15, v29, 16, 1
	v_add3_u32 v15, v29, v15, s26
	v_lshrrev_b32_e32 v15, 16, v15
	v_and_or_b32 v15, v16, s27, v15
	v_or_b32_e32 v16, s4, v73
	v_mul_u32_u24_e32 v18, 0x300, v16
	v_lshlrev_b32_e32 v48, 1, v18
	ds_read2_b32 v[16:17], v82 offset0:16 offset1:24
	v_lshl_add_u64 v[18:19], v[44:45], 0, v[48:49]
	global_store_dwordx4 v[18:19], v[12:15], off
	ds_read2_b32 v[18:19], v82 offset0:49 offset1:57
	ds_read2_b32 v[20:21], v82 offset0:82 offset1:90
	ds_read2_b32 v[22:23], v82 offset0:115 offset1:123
	s_waitcnt lgkmcnt(3)
	v_bfe_u32 v12, v16, 16, 1
	v_add3_u32 v12, v16, v12, s26
	s_waitcnt lgkmcnt(2)
	v_bfe_u32 v13, v18, 16, 1
	ds_read2_b32 v[24:25], v82 offset0:148 offset1:156
	v_lshrrev_b32_e32 v12, 16, v12
	v_add3_u32 v13, v18, v13, s26
	ds_read2_b32 v[26:27], v82 offset0:181 offset1:189
	v_and_or_b32 v12, v13, s27, v12
	s_waitcnt lgkmcnt(3)
	v_bfe_u32 v13, v20, 16, 1
	v_add3_u32 v13, v20, v13, s26
	s_waitcnt lgkmcnt(2)
	v_bfe_u32 v14, v22, 16, 1
	ds_read2_b32 v[28:29], v82 offset0:214 offset1:222
	v_lshrrev_b32_e32 v13, 16, v13
	v_add3_u32 v14, v22, v14, s26
	ds_read2_b32 v[30:31], v82 offset0:247 offset1:255
	v_and_or_b32 v13, v14, s27, v13
	s_waitcnt lgkmcnt(3)
	v_bfe_u32 v14, v24, 16, 1
	v_add3_u32 v14, v24, v14, s26
	s_waitcnt lgkmcnt(2)
	v_bfe_u32 v15, v26, 16, 1
	v_lshrrev_b32_e32 v14, 16, v14
	v_add3_u32 v15, v26, v15, s26
	v_and_or_b32 v14, v15, s27, v14
	s_waitcnt lgkmcnt(1)
	v_bfe_u32 v15, v28, 16, 1
	v_add3_u32 v15, v28, v15, s26
	s_waitcnt lgkmcnt(0)
	v_bfe_u32 v16, v30, 16, 1
	v_lshrrev_b32_e32 v15, 16, v15
	v_add3_u32 v16, v30, v16, s26
	v_and_or_b32 v15, v16, s27, v15
	v_or_b32_e32 v16, s4, v74
	v_mul_u32_u24_e32 v16, 0x300, v16
	v_lshlrev_b32_e32 v48, 1, v16
	v_lshl_add_u64 v[32:33], v[44:45], 0, v[48:49]
	global_store_dwordx4 v[32:33], v[12:15], off
	v_bfe_u32 v16, v31, 16, 1
	v_add3_u32 v16, v31, v16, s26
	v_bfe_u32 v12, v17, 16, 1
	v_add3_u32 v12, v17, v12, s26
	v_bfe_u32 v13, v19, 16, 1
	v_lshrrev_b32_e32 v12, 16, v12
	v_add3_u32 v13, v19, v13, s26
	v_and_or_b32 v12, v13, s27, v12
	v_bfe_u32 v13, v21, 16, 1
	v_add3_u32 v13, v21, v13, s26
	v_bfe_u32 v14, v23, 16, 1
	v_lshrrev_b32_e32 v13, 16, v13
	v_add3_u32 v14, v23, v14, s26
	v_and_or_b32 v13, v14, s27, v13
	v_bfe_u32 v14, v25, 16, 1
	v_add3_u32 v14, v25, v14, s26
	v_bfe_u32 v15, v27, 16, 1
	v_lshrrev_b32_e32 v14, 16, v14
	v_add3_u32 v15, v27, v15, s26
	v_and_or_b32 v14, v15, s27, v14
	v_bfe_u32 v15, v29, 16, 1
	v_add3_u32 v15, v29, v15, s26
	v_lshrrev_b32_e32 v15, 16, v15
	v_and_or_b32 v15, v16, s27, v15
	v_or_b32_e32 v16, s4, v75
	v_mul_u32_u24_e32 v16, 0x300, v16
	v_lshlrev_b32_e32 v48, 1, v16
	v_lshl_add_u64 v[16:17], v[44:45], 0, v[48:49]
	global_store_dwordx4 v[16:17], v[12:15], off
	s_waitcnt lgkmcnt(0)
	s_mov_b64 s[4:5], 0
